# v48 plus the next tile's first-K-tile B fragment LDS reads issued at epilogue entry (flagged skip in the first load part)
# baseline (speedup 1.0000x reference)
; #define PG8_STAGE(bufoff, gbase, voff) do { _Pragma("unroll") for (int _i = 0; _i < 2; ++_i) \
;         __builtin_amdgcn_global_load_lds((const unsigned*)((const char*)(gbase) + (voff)[_i]), (LAS unsigned*)(lds + (bufoff) + ldsw + _i * 8192), 16, 0, 0); } while (0)
; #define PG8_BAR __builtin_amdgcn_s_barrier()
; template <class Epi, class Sched>
; __device__ __forceinline__ void gemm_phase(LAS unsigned char* lds, const Gemm g, const Sched& S, const Epi& E) {
;     ...
;     const int wid = __builtin_amdgcn_readfirstlane(tid >> 6), lane = tid & 63, wr = wid >> 2, wc = wid & 3, fr = lane & 15, fq = lane >> 4;
;     const int K = g.K, nt = K / BK;
;     unsigned voffA[2], voffB[2];
; #pragma unroll
;     for (int i = 0; i < 2; ++i) { int R, C; stage_rc(tid * 16 + i * 8192, R, C); const int Rb = Epi::PERM ? ((R & ~31) + perm32(R & 31)) : R;
;         voffA[i] = (unsigned)(R * g.lda + C) * 2u; voffB[i] = (unsigned)(Rb * K + C) * 2u; }
;     const size_t kstep = (size_t)(BK * 2);
;     const size_t hstepA = (size_t)HALF * g.lda * 2, hstepB = (size_t)HALF * K * 2;
;     const size_t tstepA = 2 * hstepA, tstepB = 2 * hstepB;
;     const unsigned ldsw = (unsigned)wid * 1024u;
;     const int aoff = lds_byte(wr * 64 + fr, fq * 8), boff = lds_byte(wc * 32 + fr, fq * 8);
;     ...
;     Unit cur, nxt; int ui = 0;
;     if (!S.next(0, cur)) return;
;     f32x4 acc[2][2][4][2];
; #pragma unroll
;     for (int a = 0; a < 2; ++a)
; #pragma unroll
;         for (int b = 0; b < 2; ++b)
; #pragma unroll
;             for (int m = 0; m < 4; ++m)
; #pragma unroll
;                 for (int n = 0; n < 2; ++n) acc[a][b][m][n] = (f32x4){0.f, 0.f, 0.f, 0.f};
;     bf16x8 At[4][2], B0[2][2], B1[2][2];
;     const char* cA = (const char*)g.A + (size_t)cur.b * g.abs * 2 + (size_t)cur.pm * tstepA;
;     const char* cB = (const char*)g.Bt + (size_t)cur.b * g.bbs * 2 + (size_t)cur.pn * tstepB;
;     PG8_STAGE(PG8_SB(0, 0), cB, voffB); PG8_STAGE(PG8_SB(0, 1), cB + hstepB, voffB); PG8_STAGE(PG8_SA(0, 0), cA, voffA); PG8_STAGE(PG8_SA(0, 1), cA + hstepA, voffA);
;     if (wr == 1) PG8_BAR;
.LBB0_269:
	s_and_b64 vcc, exec, s[0:1]
	s_cbranch_vccz .LBB0_491
	v_readlane_b32 s0, v255, 43
	s_cmp_gt_i32 s0, 0
	s_mov_b64 s[0:1], -1
	s_cbranch_scc0 .LBB0_494
	v_readlane_b32 s0, v253, 16
	s_waitcnt vmcnt(0)
	v_mov_b32_e32 v2, v248
	v_readlane_b32 s1, v253, 17
	s_andn2_b64 vcc, exec, s[0:1]
	v_readfirstlane_b32 s4, v2
	s_cbranch_vccnz .LBB0_493
	s_mov_b32 s61, 0
	s_mov_b32 s64, 0
	v_lshlrev_b32_e32 v4, 4, v2
	v_add_u32_e32 v1, 0x2000, v4
	v_ashrrev_i32_e32 v0, 31, v1
	v_lshrrev_b32_e32 v0, 22, v0
	v_add_u32_e32 v0, v1, v0
	v_ashrrev_i32_e32 v0, 10, v0
	v_mul_i32_i24_e32 v3, 0x400, v0
	v_sub_u32_e32 v1, v1, v3
	v_lshrrev_b32_e32 v3, 4, v1
	v_bitop3_b32 v3, v3, v1, 32 bitop3:0x6c
	v_ashrrev_i32_e32 v1, 31, v3
	v_lshrrev_b32_e32 v1, 26, v1
	v_add_u32_e32 v5, v3, v1
	v_lshlrev_b32_e32 v6, 3, v0
	v_ashrrev_i32_e32 v1, 6, v5
	v_and_b32_e32 v6, -16, v6
	v_add_u32_e32 v6, v1, v6
	v_and_b32_e32 v7, 3, v1
	s_mov_b32 s0, 0x1fffe0
	v_lshrrev_b32_e32 v8, 2, v6
	v_lshlrev_b32_e32 v9, 1, v6
	v_and_b32_e32 v5, 0xc0, v5
	v_and_or_b32 v7, v6, s0, v7
	v_and_b32_e32 v8, 4, v8
	v_and_b32_e32 v9, 24, v9
	v_sub_u32_e32 v3, v3, v5
	v_mov_b32_e32 v12, 1
	v_or3_b32 v7, v7, v8, v9
	v_lshlrev_b32_e32 v8, 5, v0
	v_ashrrev_i16_sdwa v3, v12, sext(v3) dst_sel:DWORD dst_unused:UNUSED_PAD src0_sel:DWORD src1_sel:BYTE_0
	v_and_b32_e32 v8, 32, v8
	v_bfe_i32 v3, v3, 0, 16
	v_add_lshl_u32 v5, v8, v3, 1
	v_lshl_add_u32 v128, v7, 11, v5
	v_lshl_add_u32 v130, v6, 11, v5
	v_bfe_i32 v5, v2, 27, 1
	v_lshrrev_b32_e32 v5, 22, v5
	v_add_u32_e32 v5, v4, v5
	v_and_b32_e32 v5, 0xfffffc00, v5
	v_sub_u32_e32 v4, v4, v5
	v_lshrrev_b32_e32 v5, 4, v4
	v_bitop3_b32 v6, v5, v4, 32 bitop3:0x6c
	v_ashrrev_i32_e32 v5, 31, v2
	v_lshrrev_b32_e32 v5, 26, v5
	v_ashrrev_i32_e32 v4, 31, v6
	v_add_u32_e32 v5, v2, v5
	v_lshrrev_b32_e32 v4, 26, v4
	v_ashrrev_i32_e32 v5, 6, v5
	v_add_u32_e32 v7, v6, v4
	v_lshlrev_b32_e32 v8, 3, v5
	v_ashrrev_i32_e32 v4, 6, v7
	v_and_b32_e32 v8, -16, v8
	v_add_u32_e32 v8, v4, v8
	v_and_b32_e32 v9, 3, v4
	v_lshrrev_b32_e32 v10, 2, v8
	v_lshlrev_b32_e32 v11, 1, v8
	v_and_b32_e32 v7, 0xc0, v7
	v_and_or_b32 v9, v8, s0, v9
	v_and_b32_e32 v10, 4, v10
	v_and_b32_e32 v11, 24, v11
	v_sub_u32_e32 v6, v6, v7
	s_ashr_i32 s5, s4, 6
	v_or3_b32 v9, v9, v10, v11
	v_lshlrev_b32_e32 v10, 5, v5
	v_ashrrev_i16_sdwa v6, v12, sext(v6) dst_sel:DWORD dst_unused:UNUSED_PAD src0_sel:DWORD src1_sel:BYTE_0
	s_lshl_b32 s2, s5, 10
	v_and_b32_e32 v10, 32, v10
	v_bfe_i32 v6, v6, 0, 16
	v_add_lshl_u32 v7, v10, v6, 1
	s_add_i32 s52, s2, 0
	v_readlane_b32 s0, v255, 6
	v_lshl_add_u32 v132, v9, 11, v7
	s_add_i32 m0, s52, 0x10000
	v_readlane_b32 s1, v255, 7
	v_lshl_add_u32 v134, v8, 11, v7
	s_add_i32 s53, s52, 0x2000
	s_add_i32 s54, s52, 0x4000
	s_add_i32 s55, s52, 0x6000
	s_ashr_i32 s6, s4, 8
	global_load_lds_dwordx4 v132, s[0:1]
	s_add_i32 m0, s52, 0x12000
	s_nop 0
	global_load_lds_dwordx4 v128, s[0:1]
	v_readlane_b32 s0, v255, 0
	s_add_i32 m0, s52, 0x14000
	v_readlane_b32 s1, v255, 1
	s_nop 4
	global_load_lds_dwordx4 v132, s[0:1]
	s_add_i32 m0, s52, 0x16000
	s_cmp_eq_u32 s6, 1
	global_load_lds_dwordx4 v128, s[0:1]
	v_readlane_b32 s0, v255, 2
	s_mov_b32 m0, s52
	v_readlane_b32 s1, v255, 3
	s_nop 4
	global_load_lds_dwordx4 v134, s[0:1]
	s_mov_b32 m0, s53
	s_nop 0
	global_load_lds_dwordx4 v130, s[0:1]
	v_readlane_b32 s0, v255, 4
	s_mov_b32 m0, s54
	v_readlane_b32 s1, v255, 5
	s_nop 4
	global_load_lds_dwordx4 v134, s[0:1]
	s_mov_b32 m0, s55
	s_nop 0
	global_load_lds_dwordx4 v130, s[0:1]
	s_cselect_b64 s[0:1], -1, 0
	s_cmp_lg_u32 s6, 1
	s_cbranch_scc1 .LBB0_274
	s_barrier

; #define PG8_STAGE(bufoff, gbase, voff) do { _Pragma("unroll") for (int _i = 0; _i < 2; ++_i) \
;         __builtin_amdgcn_global_load_lds((const unsigned*)((const char*)(gbase) + (voff)[_i]), (LAS unsigned*)(lds + (bufoff) + ldsw + _i * 8192), 16, 0, 0); } while (0)
; #define PG8_LDA(dst, b, h) do { _Pragma("unroll") for (int m = 0; m < 4; ++m) _Pragma("unroll") for (int k = 0; k < 2; ++k) dst[m][k] = *(const LAS bf16x8*)(lds + PG8_SA(b, h) + aoff + m * 2048 + k * 1024); } while (0)
; #define PG8_LDB(dst, b, h) do { _Pragma("unroll") for (int n = 0; n < 2; ++n) _Pragma("unroll") for (int k = 0; k < 2; ++k) dst[n][k] = *(const LAS bf16x8*)(lds + PG8_SB(b, h) + boff + n * 2048 + k * 1024); } while (0)
; #define PG8_MMA(ai, bj, At, Bt) do { __builtin_amdgcn_s_setprio(1); _Pragma("unroll") for (int m = 0; m < 4; ++m) _Pragma("unroll") for (int n = 0; n < 2; ++n) _Pragma("unroll") for (int k = 0; k < 2; ++k) \
;         acc[ai][bj][m][n] = __builtin_amdgcn_mfma_f32_16x16x32_bf16(Bt[n][k], At[m][k], acc[ai][bj][m][n], 0, 0, 0); __builtin_amdgcn_s_setprio(0); } while (0)
; #define PG8_WAIT_V(n) asm volatile("s_waitcnt vmcnt(" #n ")" ::: "memory")
; #define PG8_WAIT_L(n) asm volatile("s_waitcnt lgkmcnt(" #n ")" ::: "memory")
; #define PG8_BAR __builtin_amdgcn_s_barrier()
; #define PG8_SCHED __builtin_amdgcn_sched_barrier(0)
; template <class Epi, class Sched>
; __device__ __forceinline__ void gemm_phase(LAS unsigned char* lds, const Gemm g, const Sched& S, const Epi& E) {
;     ...
;             PG8_LDB(B0, 0, 0); PG8_LDB(B1, 0, 1); PG8_SCHED; PG8_LDA(At, 0, 0); PG8_STAGE(PG8_SA(1, 1), a1 + hstepA, voffA);
;             PG8_WAIT_V(8); PG8_WAIT_L(0); PG8_BAR; PG8_MMA(0, 0, At, B0); PG8_MMA(0, 1, At, B1); PG8_BAR; PG8_SCHED;
;             PG8_LDA(At, 0, 1); PG8_STAGE(PG8_SB(0, 0), b2, voffB); PG8_STAGE(PG8_SB(0, 1), b2 + hstepB, voffB); PG8_STAGE(PG8_SA(0, 0), a2, voffA);
;             PG8_WAIT_V(8); PG8_WAIT_L(0); PG8_BAR; PG8_MMA(1, 0, At, B0); PG8_MMA(1, 1, At, B1); PG8_BAR; PG8_SCHED;
.Lp1_nobar:
	s_add_u32 s36, s24, 0xfffc0080
	s_addc_u32 s37, s25, -1
	s_mov_b32 s44, 0x10000
	v_add_u32_e32 v145, s44, v165
	s_mov_b32 s27, s42
	s_mov_b32 s26, s19
	s_mov_b32 s46, 0x14000
	ds_read_b128 v[148:151], v145
	ds_read_b128 v[152:155], v145 offset:1024
	ds_read_b128 v[156:159], v145 offset:2048
	ds_read_b128 v[160:163], v145 offset:3072
	v_add_u32_e32 v145, s46, v165
	ds_read_b128 v[168:171], v145
	ds_read_b128 v[172:175], v145 offset:1024
	ds_read_b128 v[176:179], v145 offset:2048
	ds_read_b128 v[180:183], v145 offset:3072
	s_add_i32 m0, s52, 0xc000
	ds_read_b128 v[184:187], v167
	s_cmp_eq_u32 s64, 1
	s_cbranch_scc1 .Lp1_bfrag_done
	ds_read_b128 v[188:191], v167 offset:1024
	ds_read_b128 v[192:195], v167 offset:2048
	ds_read_b128 v[196:199], v167 offset:3072
	ds_read_b128 v[200:203], v167 offset:4096
	ds_read_b128 v[204:207], v167 offset:5120
	ds_read_b128 v[208:211], v167 offset:6144
	ds_read_b128 v[214:217], v167 offset:7168
.Lp1_bfrag_done:
	s_mov_b32 s64, 0
	global_load_lds_dwordx4 v140, s[24:25]
	s_add_i32 m0, s52, 0xe000
	s_nop 0
	global_load_lds_dwordx4 v142, s[24:25]
	s_waitcnt vmcnt(8)
	s_waitcnt lgkmcnt(0)
	s_barrier
	s_setprio 1
	s_waitcnt lgkmcnt(0)
	v_mfma_f32_16x16x32_bf16 v[124:127], v[148:151], v[184:187], 0
	v_mfma_f32_16x16x32_bf16 v[120:123], v[156:159], v[184:187], 0
	v_mfma_f32_16x16x32_bf16 v[108:111], v[148:151], v[192:195], 0
	v_mfma_f32_16x16x32_bf16 v[104:107], v[156:159], v[192:195], 0
	v_mfma_f32_16x16x32_bf16 v[92:95], v[148:151], v[200:203], 0
	v_mfma_f32_16x16x32_bf16 v[88:91], v[156:159], v[200:203], 0
	v_mfma_f32_16x16x32_bf16 v[76:79], v[148:151], v[208:211], 0
	v_mfma_f32_16x16x32_bf16 v[72:75], v[156:159], v[208:211], 0
	v_mfma_f32_16x16x32_bf16 v[124:127], v[152:155], v[188:191], v[124:127]
	v_mfma_f32_16x16x32_bf16 v[120:123], v[160:163], v[188:191], v[120:123]
	v_mfma_f32_16x16x32_bf16 v[108:111], v[152:155], v[196:199], v[108:111]
	v_mfma_f32_16x16x32_bf16 v[104:107], v[160:163], v[196:199], v[104:107]
	v_mfma_f32_16x16x32_bf16 v[92:95], v[152:155], v[204:207], v[92:95]
	v_mfma_f32_16x16x32_bf16 v[88:91], v[160:163], v[204:207], v[88:91]
	v_mfma_f32_16x16x32_bf16 v[76:79], v[152:155], v[214:217], v[76:79]
	v_mfma_f32_16x16x32_bf16 v[72:75], v[160:163], v[214:217], v[72:75]
	s_setprio 0
	s_setprio 1
	v_mfma_f32_16x16x32_bf16 v[116:119], v[168:171], v[184:187], 0
	v_mfma_f32_16x16x32_bf16 v[112:115], v[176:179], v[184:187], 0
	v_mfma_f32_16x16x32_bf16 v[100:103], v[168:171], v[192:195], 0
	v_mfma_f32_16x16x32_bf16 v[96:99], v[176:179], v[192:195], 0
	v_mfma_f32_16x16x32_bf16 v[84:87], v[168:171], v[200:203], 0
	v_mfma_f32_16x16x32_bf16 v[80:83], v[176:179], v[200:203], 0
	v_mfma_f32_16x16x32_bf16 v[68:71], v[168:171], v[208:211], 0
	v_mfma_f32_16x16x32_bf16 v[64:67], v[176:179], v[208:211], 0
	v_mfma_f32_16x16x32_bf16 v[116:119], v[172:175], v[188:191], v[116:119]
	v_mfma_f32_16x16x32_bf16 v[112:115], v[180:183], v[188:191], v[112:115]
	v_mfma_f32_16x16x32_bf16 v[100:103], v[172:175], v[196:199], v[100:103]
	v_mfma_f32_16x16x32_bf16 v[96:99], v[180:183], v[196:199], v[96:99]
	v_mfma_f32_16x16x32_bf16 v[84:87], v[172:175], v[204:207], v[84:87]
	v_mfma_f32_16x16x32_bf16 v[80:83], v[180:183], v[204:207], v[80:83]
	v_mfma_f32_16x16x32_bf16 v[68:71], v[172:175], v[214:217], v[68:71]
	v_mfma_f32_16x16x32_bf16 v[64:67], v[180:183], v[214:217], v[64:67]
	s_setprio 0
	s_barrier
	s_add_i32 s44, s44, s2
	s_mov_b32 m0, s44
	ds_read_b128 v[184:187], v167 offset:16384
	ds_read_b128 v[188:191], v167 offset:17408
	ds_read_b128 v[192:195], v167 offset:18432
	ds_read_b128 v[196:199], v167 offset:19456
	ds_read_b128 v[200:203], v167 offset:20480
	ds_read_b128 v[204:207], v167 offset:21504
	ds_read_b128 v[208:211], v167 offset:22528
	ds_read_b128 v[214:217], v167 offset:23552
	global_load_lds_dwordx4 v132, s[26:27]
	s_add_i32 m0, s44, 0x2000
	s_add_u32 s44, s26, 0x40000
	s_addc_u32 s45, s27, 0
	s_add_i32 s46, s46, s2
	global_load_lds_dwordx4 v128, s[26:27]
	s_mov_b32 m0, s46
	s_nop 0
	global_load_lds_dwordx4 v132, s[44:45]
	s_add_i32 m0, s46, 0x2000
	s_nop 0
	global_load_lds_dwordx4 v128, s[44:45]
	s_mov_b32 m0, s52
	s_nop 0
	global_load_lds_dwordx4 v134, s[36:37]
	s_mov_b32 m0, s53
	s_nop 0
	global_load_lds_dwordx4 v130, s[36:37]
	s_waitcnt vmcnt(8)
	s_waitcnt lgkmcnt(0)
	s_barrier
	s_setprio 1
	s_waitcnt lgkmcnt(0)
	v_mfma_f32_16x16x32_bf16 v[60:63], v[148:151], v[184:187], 0
	v_mfma_f32_16x16x32_bf16 v[56:59], v[156:159], v[184:187], 0
	v_mfma_f32_16x16x32_bf16 v[44:47], v[148:151], v[192:195], 0
	v_mfma_f32_16x16x32_bf16 v[40:43], v[156:159], v[192:195], 0
	v_mfma_f32_16x16x32_bf16 v[28:31], v[148:151], v[200:203], 0
	v_mfma_f32_16x16x32_bf16 v[24:27], v[156:159], v[200:203], 0
	v_mfma_f32_16x16x32_bf16 v[12:15], v[148:151], v[208:211], 0
	v_mfma_f32_16x16x32_bf16 v[8:11], v[156:159], v[208:211], 0
	v_mfma_f32_16x16x32_bf16 v[60:63], v[152:155], v[188:191], v[60:63]
	v_mfma_f32_16x16x32_bf16 v[56:59], v[160:163], v[188:191], v[56:59]
	v_mfma_f32_16x16x32_bf16 v[44:47], v[152:155], v[196:199], v[44:47]
	v_mfma_f32_16x16x32_bf16 v[40:43], v[160:163], v[196:199], v[40:43]
	v_mfma_f32_16x16x32_bf16 v[28:31], v[152:155], v[204:207], v[28:31]
	v_mfma_f32_16x16x32_bf16 v[24:27], v[160:163], v[204:207], v[24:27]
	v_mfma_f32_16x16x32_bf16 v[12:15], v[152:155], v[214:217], v[12:15]
	v_mfma_f32_16x16x32_bf16 v[8:11], v[160:163], v[214:217], v[8:11]
	s_setprio 0
	s_setprio 1
	v_mfma_f32_16x16x32_bf16 v[52:55], v[168:171], v[184:187], 0
	v_mfma_f32_16x16x32_bf16 v[48:51], v[176:179], v[184:187], 0
	v_mfma_f32_16x16x32_bf16 v[36:39], v[168:171], v[192:195], 0
	v_mfma_f32_16x16x32_bf16 v[32:35], v[176:179], v[192:195], 0
	v_mfma_f32_16x16x32_bf16 v[20:23], v[168:171], v[200:203], 0
	v_mfma_f32_16x16x32_bf16 v[16:19], v[176:179], v[200:203], 0
	v_mfma_f32_16x16x32_bf16 v[4:7], v[168:171], v[208:211], 0
	v_mfma_f32_16x16x32_bf16 v[0:3], v[176:179], v[208:211], 0
	v_mfma_f32_16x16x32_bf16 v[52:55], v[172:175], v[188:191], v[52:55]
	v_mfma_f32_16x16x32_bf16 v[48:51], v[180:183], v[188:191], v[48:51]
	v_mfma_f32_16x16x32_bf16 v[36:39], v[172:175], v[196:199], v[36:39]
	v_mfma_f32_16x16x32_bf16 v[32:35], v[180:183], v[196:199], v[32:35]
	v_mfma_f32_16x16x32_bf16 v[20:23], v[172:175], v[204:207], v[20:23]
	v_mfma_f32_16x16x32_bf16 v[16:19], v[180:183], v[204:207], v[16:19]
	v_mfma_f32_16x16x32_bf16 v[4:7], v[172:175], v[214:217], v[4:7]
	v_mfma_f32_16x16x32_bf16 v[0:3], v[180:183], v[214:217], v[0:3]
	s_setprio 0
	s_barrier
; #define PG8_STAGE(bufoff, gbase, voff) do { _Pragma("unroll") for (int _i = 0; _i < 2; ++_i) \
;         __builtin_amdgcn_global_load_lds((const unsigned*)((const char*)(gbase) + (voff)[_i]), (LAS unsigned*)(lds + (bufoff) + ldsw + _i * 8192), 16, 0, 0); } while (0)
; #define PG8_LDA(dst, b, h) do { _Pragma("unroll") for (int m = 0; m < 4; ++m) _Pragma("unroll") for (int k = 0; k < 2; ++k) dst[m][k] = *(const LAS bf16x8*)(lds + PG8_SA(b, h) + aoff + m * 2048 + k * 1024); } while (0)
; #define PG8_LDB(dst, b, h) do { _Pragma("unroll") for (int n = 0; n < 2; ++n) _Pragma("unroll") for (int k = 0; k < 2; ++k) dst[n][k] = *(const LAS bf16x8*)(lds + PG8_SB(b, h) + boff + n * 2048 + k * 1024); } while (0)
; #define PG8_MMA(ai, bj, At, Bt) do { __builtin_amdgcn_s_setprio(1); _Pragma("unroll") for (int m = 0; m < 4; ++m) _Pragma("unroll") for (int n = 0; n < 2; ++n) _Pragma("unroll") for (int k = 0; k < 2; ++k) \
;         acc[ai][bj][m][n] = __builtin_amdgcn_mfma_f32_16x16x32_bf16(Bt[n][k], At[m][k], acc[ai][bj][m][n], 0, 0, 0); __builtin_amdgcn_s_setprio(0); } while (0)
; #define PG8_WAIT_V(n) asm volatile("s_waitcnt vmcnt(" #n ")" ::: "memory")
; #define PG8_WAIT_L(n) asm volatile("s_waitcnt lgkmcnt(" #n ")" ::: "memory")
; #define PG8_BAR __builtin_amdgcn_s_barrier()
; #define PG8_SCHED __builtin_amdgcn_sched_barrier(0)
; template <class Epi, class Sched>
; __device__ __forceinline__ void gemm_phase(LAS unsigned char* lds, const Gemm g, const Sched& S, const Epi& E) {
;     ...
;             PG8_LDB(B0, 1, 0); PG8_LDB(B1, 1, 1); PG8_SCHED; PG8_LDA(At, 1, 0); PG8_STAGE(PG8_SA(0, 1), a2 + hstepA, voffA);
;             PG8_WAIT_V(8); PG8_WAIT_L(0); PG8_BAR; PG8_MMA(0, 0, At, B0); PG8_MMA(0, 1, At, B1); PG8_BAR; PG8_SCHED;
;             PG8_LDA(At, 1, 1); PG8_STAGE(PG8_SB(1, 0), b3, voffB); PG8_STAGE(PG8_SB(1, 1), b3 + hstepB, voffB); PG8_STAGE(PG8_SA(1, 0), a3, voffA);
;             PG8_WAIT_V(8); PG8_WAIT_L(0); PG8_BAR; PG8_MMA(1, 0, At, B0); PG8_MMA(1, 1, At, B1); PG8_BAR; PG8_SCHED;
	s_add_i32 s44, 0, 0x18000
	v_add_u32_e32 v145, s44, v165
	s_add_i32 s45, 0, 0x1c000
	ds_read_b128 v[148:151], v145
	ds_read_b128 v[152:155], v145 offset:1024
	ds_read_b128 v[156:159], v145 offset:2048
	ds_read_b128 v[160:163], v145 offset:3072
	v_add_u32_e32 v145, s45, v165
	ds_read_b128 v[168:171], v145
	ds_read_b128 v[172:175], v145 offset:1024
	ds_read_b128 v[176:179], v145 offset:2048
	ds_read_b128 v[180:183], v145 offset:3072
	s_add_u32 s36, s36, 0x40000
	s_addc_u32 s37, s37, 0
	s_mov_b32 m0, s54
	ds_read_b128 v[184:187], v167 offset:32768
	ds_read_b128 v[188:191], v167 offset:33792
	ds_read_b128 v[192:195], v167 offset:34816
	ds_read_b128 v[196:199], v167 offset:35840
	ds_read_b128 v[200:203], v167 offset:36864
	ds_read_b128 v[204:207], v167 offset:37888
	ds_read_b128 v[208:211], v167 offset:38912
	ds_read_b128 v[214:217], v167 offset:39936
	global_load_lds_dwordx4 v134, s[36:37]
	s_mov_b32 m0, s55
	s_nop 0
	global_load_lds_dwordx4 v130, s[36:37]
	s_waitcnt vmcnt(8)
	s_waitcnt lgkmcnt(0)
	s_barrier
	s_setprio 1
	s_waitcnt lgkmcnt(0)
	v_mfma_f32_16x16x32_bf16 v[124:127], v[148:151], v[184:187], v[124:127]
	v_mfma_f32_16x16x32_bf16 v[120:123], v[156:159], v[184:187], v[120:123]
	v_mfma_f32_16x16x32_bf16 v[108:111], v[148:151], v[192:195], v[108:111]
	v_mfma_f32_16x16x32_bf16 v[104:107], v[156:159], v[192:195], v[104:107]
	v_mfma_f32_16x16x32_bf16 v[92:95], v[148:151], v[200:203], v[92:95]
	v_mfma_f32_16x16x32_bf16 v[88:91], v[156:159], v[200:203], v[88:91]
	v_mfma_f32_16x16x32_bf16 v[76:79], v[148:151], v[208:211], v[76:79]
	v_mfma_f32_16x16x32_bf16 v[72:75], v[156:159], v[208:211], v[72:75]
	v_mfma_f32_16x16x32_bf16 v[124:127], v[152:155], v[188:191], v[124:127]
	v_mfma_f32_16x16x32_bf16 v[120:123], v[160:163], v[188:191], v[120:123]
	v_mfma_f32_16x16x32_bf16 v[108:111], v[152:155], v[196:199], v[108:111]
	v_mfma_f32_16x16x32_bf16 v[104:107], v[160:163], v[196:199], v[104:107]
	v_mfma_f32_16x16x32_bf16 v[92:95], v[152:155], v[204:207], v[92:95]
	v_mfma_f32_16x16x32_bf16 v[88:91], v[160:163], v[204:207], v[88:91]
	v_mfma_f32_16x16x32_bf16 v[76:79], v[152:155], v[214:217], v[76:79]
	v_mfma_f32_16x16x32_bf16 v[72:75], v[160:163], v[214:217], v[72:75]
	s_setprio 0
	s_setprio 1
	v_mfma_f32_16x16x32_bf16 v[116:119], v[168:171], v[184:187], v[116:119]
	v_mfma_f32_16x16x32_bf16 v[112:115], v[176:179], v[184:187], v[112:115]
	v_mfma_f32_16x16x32_bf16 v[100:103], v[168:171], v[192:195], v[100:103]
	v_mfma_f32_16x16x32_bf16 v[96:99], v[176:179], v[192:195], v[96:99]
	v_mfma_f32_16x16x32_bf16 v[84:87], v[168:171], v[200:203], v[84:87]
	v_mfma_f32_16x16x32_bf16 v[80:83], v[176:179], v[200:203], v[80:83]
	v_mfma_f32_16x16x32_bf16 v[68:71], v[168:171], v[208:211], v[68:71]
	v_mfma_f32_16x16x32_bf16 v[64:67], v[176:179], v[208:211], v[64:67]
	v_mfma_f32_16x16x32_bf16 v[116:119], v[172:175], v[188:191], v[116:119]
	v_mfma_f32_16x16x32_bf16 v[112:115], v[180:183], v[188:191], v[112:115]
	v_mfma_f32_16x16x32_bf16 v[100:103], v[172:175], v[196:199], v[100:103]
	v_mfma_f32_16x16x32_bf16 v[96:99], v[180:183], v[196:199], v[96:99]
	v_mfma_f32_16x16x32_bf16 v[84:87], v[172:175], v[204:207], v[84:87]
	v_mfma_f32_16x16x32_bf16 v[80:83], v[180:183], v[204:207], v[80:83]
	v_mfma_f32_16x16x32_bf16 v[68:71], v[172:175], v[214:217], v[68:71]
	v_mfma_f32_16x16x32_bf16 v[64:67], v[180:183], v[214:217], v[64:67]
	s_setprio 0
	s_barrier
	s_add_u32 s98, s36, 0xfffc0080
	s_addc_u32 s99, s37, -1
	s_add_u32 s62, s26, 0x80
	s_addc_u32 s63, s27, 0
	s_add_i32 s36, s44, s2
	s_mov_b32 m0, s36
	ds_read_b128 v[184:187], v167 offset:49152
	ds_read_b128 v[188:191], v167 offset:50176
	ds_read_b128 v[192:195], v167 offset:51200
	ds_read_b128 v[196:199], v167 offset:52224
	ds_read_b128 v[200:203], v167 offset:53248
	ds_read_b128 v[204:207], v167 offset:54272
	ds_read_b128 v[208:211], v167 offset:55296
	ds_read_b128 v[214:217], v167 offset:56320
	global_load_lds_dwordx4 v132, s[62:63]
	s_add_i32 m0, s36, 0x2000
	s_add_u32 s26, s26, 0x40080
	s_addc_u32 s27, s27, 0
	s_add_i32 s36, s45, s2
	global_load_lds_dwordx4 v128, s[62:63]
	s_mov_b32 m0, s36
	s_nop 0
	global_load_lds_dwordx4 v132, s[26:27]
	s_add_i32 m0, s36, 0x2000
	s_nop 0
	global_load_lds_dwordx4 v128, s[26:27]
	s_mov_b32 m0, s56
	s_nop 0
	global_load_lds_dwordx4 v134, s[98:99]
	s_mov_b32 m0, s57
	s_nop 0
	global_load_lds_dwordx4 v130, s[98:99]
	s_waitcnt vmcnt(8)
	s_waitcnt lgkmcnt(0)
	s_barrier
	s_setprio 1
	s_waitcnt lgkmcnt(0)
	v_mfma_f32_16x16x32_bf16 v[60:63], v[148:151], v[184:187], v[60:63]
	v_mfma_f32_16x16x32_bf16 v[56:59], v[156:159], v[184:187], v[56:59]
	v_mfma_f32_16x16x32_bf16 v[44:47], v[148:151], v[192:195], v[44:47]
	v_mfma_f32_16x16x32_bf16 v[40:43], v[156:159], v[192:195], v[40:43]
	v_mfma_f32_16x16x32_bf16 v[28:31], v[148:151], v[200:203], v[28:31]
	v_mfma_f32_16x16x32_bf16 v[24:27], v[156:159], v[200:203], v[24:27]
	v_mfma_f32_16x16x32_bf16 v[12:15], v[148:151], v[208:211], v[12:15]
	v_mfma_f32_16x16x32_bf16 v[8:11], v[156:159], v[208:211], v[8:11]
	v_mfma_f32_16x16x32_bf16 v[60:63], v[152:155], v[188:191], v[60:63]
	v_mfma_f32_16x16x32_bf16 v[56:59], v[160:163], v[188:191], v[56:59]
	v_mfma_f32_16x16x32_bf16 v[44:47], v[152:155], v[196:199], v[44:47]
	v_mfma_f32_16x16x32_bf16 v[40:43], v[160:163], v[196:199], v[40:43]
	v_mfma_f32_16x16x32_bf16 v[28:31], v[152:155], v[204:207], v[28:31]
	v_mfma_f32_16x16x32_bf16 v[24:27], v[160:163], v[204:207], v[24:27]
	v_mfma_f32_16x16x32_bf16 v[12:15], v[152:155], v[214:217], v[12:15]
	v_mfma_f32_16x16x32_bf16 v[8:11], v[160:163], v[214:217], v[8:11]
	s_setprio 0
	s_setprio 1
	v_mfma_f32_16x16x32_bf16 v[52:55], v[168:171], v[184:187], v[52:55]
	v_mfma_f32_16x16x32_bf16 v[48:51], v[176:179], v[184:187], v[48:51]
	v_mfma_f32_16x16x32_bf16 v[36:39], v[168:171], v[192:195], v[36:39]
	v_mfma_f32_16x16x32_bf16 v[32:35], v[176:179], v[192:195], v[32:35]
	v_mfma_f32_16x16x32_bf16 v[20:23], v[168:171], v[200:203], v[20:23]
	v_mfma_f32_16x16x32_bf16 v[16:19], v[176:179], v[200:203], v[16:19]
	v_mfma_f32_16x16x32_bf16 v[4:7], v[168:171], v[208:211], v[4:7]
	v_mfma_f32_16x16x32_bf16 v[0:3], v[176:179], v[208:211], v[0:3]
	v_mfma_f32_16x16x32_bf16 v[52:55], v[172:175], v[188:191], v[52:55]
	v_mfma_f32_16x16x32_bf16 v[48:51], v[180:183], v[188:191], v[48:51]
	v_mfma_f32_16x16x32_bf16 v[36:39], v[172:175], v[196:199], v[36:39]
	v_mfma_f32_16x16x32_bf16 v[32:35], v[180:183], v[196:199], v[32:35]
	v_mfma_f32_16x16x32_bf16 v[20:23], v[172:175], v[204:207], v[20:23]
	v_mfma_f32_16x16x32_bf16 v[16:19], v[180:183], v[204:207], v[16:19]
	v_mfma_f32_16x16x32_bf16 v[4:7], v[172:175], v[214:217], v[4:7]
	v_mfma_f32_16x16x32_bf16 v[0:3], v[180:183], v[214:217], v[0:3]
	s_setprio 0
	s_barrier
	s_add_i32 s43, s43, 2
	s_add_u32 s24, s24, 0x100
	s_addc_u32 s25, s25, 0
	s_add_u32 s19, s19, 0x100
	s_addc_u32 s42, s42, 0

;     __device__ __forceinline__ void operator()(f32x4 (&acc)[2][2][4][2], const Unit& u, int wr, int wc, int fr, int fq) const {
;         const int pn = u.pn;
;         int mode; size_t ocol;
;         if (pn < 8)       { mode = 4; ocol = S_YA + pn * 128; }
;         else if (pn < 12) { mode = 1; ocol = S_GV + (pn - 8) * 256; }
;         else if (pn < 16) { mode = 0; ocol = S_BP + (pn - 12) * 256; }
;         else if (pn < 24) { mode = 5; ocol = S_Q + (pn - 16) * 128; }
;         else if (pn < 32) { mode = 6; ocol = S_CBZ + (pn - 24) * 128; }
;         else              { mode = 7; ocol = 0; }
;         if (mode == 7) {
;     ...
;         const int row0 = u.pm * BM + wr * 64 + fr; const size_t col0 = ocol + wc * 32 + 8 * fq;
.LBB0_283:
	ds_read_b128 v[188:191], v167 offset:1024
	ds_read_b128 v[192:195], v167 offset:2048
	ds_read_b128 v[196:199], v167 offset:3072
	ds_read_b128 v[200:203], v167 offset:4096
	ds_read_b128 v[204:207], v167 offset:5120
	ds_read_b128 v[208:211], v167 offset:6144
	ds_read_b128 v[214:217], v167 offset:7168
	s_mov_b32 s64, 1
	s_cmp_gt_u32 s59, 31
	s_cbranch_scc1 .LBB0_424
	v_lshlrev_b32_e32 v150, 11, v164
	v_lshl_add_u32 v150, v136, 1, v150
	s_lshl_b32 s14, s60, 19
	s_add_u32 s24, s70, s14
	s_addc_u32 s25, s71, 0
	s_cmp_lt_u32 s59, 8
	s_cbranch_scc1 .Lp1_epi_m4
	s_cmp_lt_u32 s59, 12
	s_cbranch_scc1 .Lp1_epi_m1
	s_cmp_lt_u32 s59, 16
	s_cbranch_scc1 .Lp1_epi_m0
	s_cmp_lt_u32 s59, 24
	s_cbranch_scc1 .Lp1_epi_m5

; #define PG8_WAIT_V(n) asm volatile("s_waitcnt vmcnt(" #n ")" ::: "memory")
; #define PG8_BAR __builtin_amdgcn_s_barrier()
; template <class Epi, class Sched>
; __device__ __forceinline__ void gemm_phase(LAS unsigned char* lds, const Gemm g, const Sched& S, const Epi& E) {
;     ...
;     PG8_WAIT_V(0);
;     PG8_BAR;
.LBB0_492:
	s_waitcnt vmcnt(0)
	v_readlane_b32 s24, v255, 38
	v_readlane_b32 s25, v255, 39
	s_mul_i32 s27, s96, 24
	s_waitcnt lgkmcnt(0)
	s_barrier
